# v26_pv0
# baseline (speedup 1.0000x reference)
; #define LAS __attribute__((address_space(3)))
; __device__ __forceinline__ void phase_attn(const Params& p, int l, LAS unsigned char* lds, int bid, int G, int tid) {
;     ...
;                     const int qb = 2 * qh + blk; int ks0 = 16 * qb - 8; ks0 = ks0 < 0 ? 0 : ks0; ks0 = ks0 > 32 ? 32 : ks0;
;                     f32x4 St[2];
; #pragma unroll
;                     for (int nb = 0; nb < 2; ++nb) { f32x4 a0 = {0.f, 0.f, 0.f, 0.f};
; #pragma unroll
;                         for (int ks = 0; ks < 4; ++ks) { const bf16x8 kf = *(const LAS bf16x8*)(Kt + (ks0 + nb * 16 + fr) * 272 + (ks * 32 + g * 8) * 2);
;                             a0 = __builtin_amdgcn_mfma_f32_16x16x32_bf16(kf, Qf[blk][ks], a0, 0, 0, 0); }
;                         St[nb] = a0; }
;                     const int qc = qb * 16 + fr; int cs = qc - 8; cs = cs < 0 ? 0 : cs; cs = cs > 48 ? 48 : cs;
;                     float mt = -INFINITY;
; #pragma unroll
;                     for (int nb = 0; nb < 2; ++nb)
; #pragma unroll
;                         for (int j = 0; j < 4; ++j) { const int kc = ks0 + nb * 16 + g * 4 + j; const bool ok = (kc >= cs) && (kc < cs + 16);
;                             int dc = kc - qc; dc = dc < -15 ? -15 : dc; dc = dc > 15 ? 15 : dc;
;                             const float sv = ok ? St[nb][j] + rp[dc + 15] : -INFINITY; St[nb][j] = sv; mt = fmaxf(mt, sv); }
;                     mt = fmaxf(mt, __shfl_xor(mt, 16)); mt = fmaxf(mt, __shfl_xor(mt, 32));
;                     const float mnew = fmaxf(mrun[blk], mt), alpha = __expf(mrun[blk] - mnew);
;                     float psum = 0.f;
; #pragma unroll
;                     for (int nb = 0; nb < 2; ++nb)
; #pragma unroll
;                         for (int j = 0; j < 4; ++j) { const float pe = __expf(St[nb][j] - mnew); St[nb][j] = pe; psum += pe; }
;                     lrun[blk] = lrun[blk] * alpha + psum; mrun[blk] = mnew;
;                     u32x4 pv; pv.x = pk2(St[0][0], St[0][1]); pv.y = pk2(St[0][2], St[0][3]); pv.z = pk2(St[1][0], St[1][1]); pv.w = pk2(St[1][2], St[1][3]);
;                     const bf16x8 Pf = __builtin_bit_cast(bf16x8, pv);
; #pragma unroll
;                     for (int db = 0; db < 8; ++db) { const LAS unsigned char* vp = Vt + (db * 16 + fr) * 144 + (ks0 + g * 4) * 2;
;                         const u32x2 lo = *(const LAS u32x2*)(vp), hi = *(const LAS u32x2*)(vp + 32);
.LBB0_247:
	s_movk_i32 s45, 0x1400
	s_add_i32 s4, s18, s94
	v_cmp_ge_u32_e32 vcc, s4, v135
	v_cmp_lt_u32_e64 s[4:5], s4, v137
	s_and_b64 s[40:41], vcc, s[4:5]
	s_waitcnt lgkmcnt(0)
	s_barrier
	s_and_saveexec_b64 s[4:5], s[40:41]
	s_cbranch_execz .LBB0_244
	ds_read_b128 v[116:119], v209
	ds_read_b128 v[120:123], v209 offset:64
	ds_read_b128 v[234:237], v209 offset:128
	ds_read_b128 v[238:241], v209 offset:192
	ds_read_b128 v[242:245], v209 offset:4352
	ds_read_b128 v[212:215], v209 offset:4416
	ds_read_b128 v[246:249], v209 offset:4480
	s_waitcnt lgkmcnt(6)
	v_mfma_f32_16x16x32_bf16 v[116:119], v[116:119], v[4:7], 0
	s_waitcnt lgkmcnt(5)
	v_mfma_f32_16x16x32_bf16 v[116:119], v[120:123], v[8:11], v[116:119]
	s_waitcnt lgkmcnt(4)
	v_mfma_f32_16x16x32_bf16 v[116:119], v[234:237], v[12:15], v[116:119]
	ds_read_b128 v[234:237], v209 offset:4544
	s_waitcnt lgkmcnt(4)
	v_mfma_f32_16x16x32_bf16 v[116:119], v[238:241], v[16:19], v[116:119]
	s_waitcnt lgkmcnt(3)
	v_mfma_f32_16x16x32_bf16 v[120:123], v[242:245], v[4:7], 0
	s_waitcnt lgkmcnt(2)
	v_mfma_f32_16x16x32_bf16 v[120:123], v[212:215], v[8:11], v[120:123]
	s_waitcnt lgkmcnt(1)
	v_mfma_f32_16x16x32_bf16 v[120:123], v[246:249], v[12:15], v[120:123]
	s_waitcnt lgkmcnt(0)
	v_mfma_f32_16x16x32_bf16 v[120:123], v[234:237], v[16:19], v[120:123]
	v_add_u32_e32 v234, v1, v174
	v_add_u32_e32 v235, v1, v175
	v_add_u32_e32 v236, v1, v176
	v_add_u32_e32 v237, v1, v177
	v_add_u32_e32 v238, v1, v195
	v_add_u32_e32 v239, v1, v196
	v_add_u32_e32 v240, v1, v197
	v_add_u32_e32 v241, v1, v198
	ds_read_b32 v234, v234 offset:36892
	ds_read_b32 v235, v235 offset:36892
	ds_read_b32 v236, v236 offset:36892
	ds_read_b32 v237, v237 offset:36892
	ds_read_b32 v238, v238 offset:36892
	ds_read_b32 v239, v239 offset:36892
	ds_read_b32 v240, v240 offset:36892
	ds_read_b32 v241, v241 offset:36892
	v_mov_b32_e32 v248, 0xff800000
	s_waitcnt lgkmcnt(0)
	v_add_f32_e32 v234, v116, v234
	v_add_f32_e32 v235, v117, v235
	v_add_f32_e32 v236, v118, v236
	v_add_f32_e32 v237, v119, v237
	v_add_f32_e32 v238, v120, v238
	v_add_f32_e32 v239, v121, v239
	v_add_f32_e32 v240, v122, v240
	v_add_f32_e32 v241, v123, v241
	v_cndmask_b32_e64 v214, v248, v234, s[8:9]
	v_cndmask_b32_e64 v215, v248, v235, s[10:11]
	v_cndmask_b32_e64 v224, v248, v236, s[12:13]
	v_cndmask_b32_e64 v116, v248, v237, s[24:25]
	v_cndmask_b32_e64 v118, v248, v238, s[26:27]
	v_cndmask_b32_e64 v117, v248, v239, s[28:29]
	v_cndmask_b32_e64 v120, v248, v240, s[30:31]
	v_cndmask_b32_e64 v119, v248, v241, s[34:35]
	v_mov_b32_e32 v213, 0xff800000
	v_max3_f32 v121, v214, v213, v215
	v_max3_f32 v121, v121, v224, v116
	v_max3_f32 v121, v121, v118, v117
	v_max3_f32 v121, v121, v120, v119
	ds_bpermute_b32 v122, v169, v121
	v_add_u32_e32 v220, v167, v144
	s_waitcnt lgkmcnt(0)
	v_max_f32_e32 v122, v122, v122
	v_max_f32_e32 v121, v121, v122
	ds_bpermute_b32 v122, v170, v121
	s_waitcnt lgkmcnt(0)
	v_max3_f32 v212, v142, v121, v122
	v_sub_f32_e32 v116, v116, v212
	v_sub_f32_e32 v122, v214, v212
	v_mul_f32_e32 v116, 0x3fb8aa3b, v116
	v_mul_f32_e32 v122, 0x3fb8aa3b, v122
	v_exp_f32_e32 v225, v116
	v_sub_f32_e32 v116, v118, v212
	v_exp_f32_e32 v214, v122
	v_sub_f32_e32 v122, v215, v212
	v_mul_f32_e32 v116, 0x3fb8aa3b, v116
	v_mul_f32_e32 v122, 0x3fb8aa3b, v122
	v_exp_f32_e32 v226, v116
	v_sub_f32_e32 v116, v117, v212
	v_sub_f32_e32 v121, v142, v212
	v_exp_f32_e32 v215, v122
	v_sub_f32_e32 v122, v224, v212
	v_mul_f32_e32 v116, 0x3fb8aa3b, v116
	v_mul_f32_e32 v121, 0x3fb8aa3b, v121
	v_mul_f32_e32 v122, 0x3fb8aa3b, v122
	v_exp_f32_e32 v227, v116
	v_sub_f32_e32 v116, v120, v212
	v_add_u32_e32 v120, 0x4000, v220
	v_exp_f32_e32 v224, v122
	v_exp_f32_e32 v142, v121
	ds_read2_b64 v[120:123], v120 offset0:128 offset1:132
	v_add_u32_e32 v234, 0x4800, v220
	ds_read2_b64 v[234:237], v234 offset0:160 offset1:164
	v_add_u32_e32 v238, 0x5000, v220
	ds_read2_b64 v[238:241], v238 offset0:192 offset1:196
	v_add_u32_e32 v242, 0x5800, v220
	ds_read2_b64 v[242:245], v242 offset0:224 offset1:228
	v_add_u32_e32 v246, 0x6800, v220
	ds_read2_b64 v[246:249], v246 offset1:4
	v_mul_f32_e32 v116, 0x3fb8aa3b, v116
	v_exp_f32_e32 v228, v116
	v_sub_f32_e32 v116, v119, v212
	v_mul_f32_e32 v116, 0x3fb8aa3b, v116
	v_pk_mul_f32 v[54:55], v[54:55], v[142:143] op_sel_hi:[1,0]
	v_pk_mul_f32 v[52:53], v[52:53], v[142:143] op_sel_hi:[1,0]
	v_exp_f32_e32 v229, v116
	v_cvt_pk_bf16_f32 v116, v214, v215
	v_cvt_pk_bf16_f32 v117, v224, v225
	v_cvt_pk_bf16_f32 v118, v226, v227
	v_cvt_pk_bf16_f32 v119, v228, v229
	v_pk_mul_f32 v[58:59], v[58:59], v[142:143] op_sel_hi:[1,0]
	s_waitcnt lgkmcnt(4)
; #define LAS __attribute__((address_space(3)))
; __device__ __forceinline__ void phase_attn(const Params& p, int l, LAS unsigned char* lds, int bid, int G, int tid) {
;     ...
;                     const int qb = 2 * qh + blk; int ks0 = 16 * qb - 8; ks0 = ks0 < 0 ? 0 : ks0; ks0 = ks0 > 32 ? 32 : ks0;
;                     f32x4 St[2];
; #pragma unroll
;                     for (int nb = 0; nb < 2; ++nb) { f32x4 a0 = {0.f, 0.f, 0.f, 0.f};
; #pragma unroll
;                         for (int ks = 0; ks < 4; ++ks) { const bf16x8 kf = *(const LAS bf16x8*)(Kt + (ks0 + nb * 16 + fr) * 272 + (ks * 32 + g * 8) * 2);
;                             a0 = __builtin_amdgcn_mfma_f32_16x16x32_bf16(kf, Qf[blk][ks], a0, 0, 0, 0); }
;                         St[nb] = a0; }
;                     const int qc = qb * 16 + fr; int cs = qc - 8; cs = cs < 0 ? 0 : cs; cs = cs > 48 ? 48 : cs;
;                     float mt = -INFINITY;
; #pragma unroll
;                     for (int nb = 0; nb < 2; ++nb)
; #pragma unroll
;                         for (int j = 0; j < 4; ++j) { const int kc = ks0 + nb * 16 + g * 4 + j; const bool ok = (kc >= cs) && (kc < cs + 16);
;                             int dc = kc - qc; dc = dc < -15 ? -15 : dc; dc = dc > 15 ? 15 : dc;
;                             const float sv = ok ? St[nb][j] + rp[dc + 15] : -INFINITY; St[nb][j] = sv; mt = fmaxf(mt, sv); }
;                     mt = fmaxf(mt, __shfl_xor(mt, 16)); mt = fmaxf(mt, __shfl_xor(mt, 32));
;                     const float mnew = fmaxf(mrun[blk], mt), alpha = __expf(mrun[blk] - mnew);
;                     float psum = 0.f;
; #pragma unroll
;                     for (int nb = 0; nb < 2; ++nb)
; #pragma unroll
;                         for (int j = 0; j < 4; ++j) { const float pe = __expf(St[nb][j] - mnew); St[nb][j] = pe; psum += pe; }
;                     lrun[blk] = lrun[blk] * alpha + psum; mrun[blk] = mnew;
;                     u32x4 pv; pv.x = pk2(St[0][0], St[0][1]); pv.y = pk2(St[0][2], St[0][3]); pv.z = pk2(St[1][0], St[1][1]); pv.w = pk2(St[1][2], St[1][3]);
;                     const bf16x8 Pf = __builtin_bit_cast(bf16x8, pv);
; #pragma unroll
;                     for (int db = 0; db < 8; ++db) { const LAS unsigned char* vp = Vt + (db * 16 + fr) * 144 + (ks0 + g * 4) * 2;
;                         const u32x2 lo = *(const LAS u32x2*)(vp), hi = *(const LAS u32x2*)(vp + 32);
	v_mfma_f32_16x16x32_bf16 v[52:55], v[120:123], v[116:119], v[52:55]
	v_add_u32_e32 v120, 0x7000, v220
	ds_read2_b64 v[120:123], v120 offset0:32 offset1:36
	v_pk_mul_f32 v[56:57], v[56:57], v[142:143] op_sel_hi:[1,0]
	v_pk_mul_f32 v[62:63], v[62:63], v[142:143] op_sel_hi:[1,0]
	v_pk_mul_f32 v[60:61], v[60:61], v[142:143] op_sel_hi:[1,0]
	s_waitcnt lgkmcnt(4)
	v_mfma_f32_16x16x32_bf16 v[56:59], v[234:237], v[116:119], v[56:59]
	v_add_u32_e32 v234, 0x7800, v220
	ds_read2_b64 v[234:237], v234 offset0:64 offset1:68
	v_pk_mul_f32 v[66:67], v[66:67], v[142:143] op_sel_hi:[1,0]
	s_waitcnt lgkmcnt(4)
	v_mfma_f32_16x16x32_bf16 v[60:63], v[238:241], v[116:119], v[60:63]
	v_add_u32_e32 v238, 0x8000, v220
	ds_read2_b64 v[238:241], v238 offset0:96 offset1:100
	v_pk_mul_f32 v[64:65], v[64:65], v[142:143] op_sel_hi:[1,0]
	v_pk_mul_f32 v[74:75], v[74:75], v[142:143] op_sel_hi:[1,0]
	v_pk_mul_f32 v[72:73], v[72:73], v[142:143] op_sel_hi:[1,0]
	s_waitcnt lgkmcnt(4)
	v_mfma_f32_16x16x32_bf16 v[64:67], v[242:245], v[116:119], v[64:67]
	v_pk_mul_f32 v[82:83], v[82:83], v[142:143] op_sel_hi:[1,0]
	s_waitcnt lgkmcnt(3)
	v_mfma_f32_16x16x32_bf16 v[72:75], v[246:249], v[116:119], v[72:75]
	v_pk_mul_f32 v[80:81], v[80:81], v[142:143] op_sel_hi:[1,0]
	v_pk_mul_f32 v[70:71], v[70:71], v[142:143] op_sel_hi:[1,0]
	v_pk_mul_f32 v[68:69], v[68:69], v[142:143] op_sel_hi:[1,0]
	s_waitcnt lgkmcnt(2)
	v_mfma_f32_16x16x32_bf16 v[80:83], v[120:123], v[116:119], v[80:83]
	v_pk_mul_f32 v[78:79], v[78:79], v[142:143] op_sel_hi:[1,0]
	s_waitcnt lgkmcnt(1)
	v_mfma_f32_16x16x32_bf16 v[68:71], v[234:237], v[116:119], v[68:71]
	v_pk_mul_f32 v[76:77], v[76:77], v[142:143] op_sel_hi:[1,0]
	v_add_u32_e32 v220, v166, v153
	ds_read_b128 v[230:233], v220 offset:4416
	s_waitcnt lgkmcnt(1)
	v_mfma_f32_16x16x32_bf16 v[76:79], v[238:241], v[116:119], v[76:79]
	ds_read_b128 v[116:119], v220
	ds_read_b128 v[120:123], v220 offset:64
	s_waitcnt lgkmcnt(1)
	v_mfma_f32_16x16x32_bf16 v[116:119], v[116:119], v[20:23], 0
	s_waitcnt lgkmcnt(0)
	v_mfma_f32_16x16x32_bf16 v[116:119], v[120:123], v[24:27], v[116:119]
	ds_read_b128 v[120:123], v220 offset:128
	s_waitcnt lgkmcnt(0)
	v_mfma_f32_16x16x32_bf16 v[116:119], v[120:123], v[28:31], v[116:119]
	ds_read_b128 v[120:123], v220 offset:192
	s_waitcnt lgkmcnt(0)
	v_mfma_f32_16x16x32_bf16 v[120:123], v[120:123], v[32:35], v[116:119]
	s_nop 4
	ds_read_b128 v[116:119], v220 offset:4352
	s_waitcnt lgkmcnt(0)
	v_mfma_f32_16x16x32_bf16 v[116:119], v[116:119], v[20:23], 0
	v_mfma_f32_16x16x32_bf16 v[116:119], v[230:233], v[24:27], v[116:119]
	ds_read_b128 v[230:233], v220 offset:4480
	s_waitcnt lgkmcnt(0)
	v_mfma_f32_16x16x32_bf16 v[116:119], v[230:233], v[28:31], v[116:119]
	ds_read_b128 v[230:233], v220 offset:4544
	s_waitcnt lgkmcnt(0)
	v_mfma_f32_16x16x32_bf16 v[116:119], v[230:233], v[32:35], v[116:119]
	v_add_u32_e32 v234, v1, v199
	v_add_u32_e32 v235, v1, v200
	v_add_u32_e32 v236, v1, v201
	v_add_u32_e32 v237, v1, v202
	v_add_u32_e32 v238, v1, v203
	v_add_u32_e32 v239, v1, v204
	v_add_u32_e32 v240, v1, v205
	v_add_u32_e32 v241, v1, v206
	ds_read_b32 v234, v234 offset:36892
	ds_read_b32 v235, v235 offset:36892
	ds_read_b32 v236, v236 offset:36892
	ds_read_b32 v237, v237 offset:36892
	ds_read_b32 v238, v238 offset:36892
	ds_read_b32 v239, v239 offset:36892
	ds_read_b32 v240, v240 offset:36892
	ds_read_b32 v241, v241 offset:36892
	v_mov_b32_e32 v248, 0xff800000
	s_waitcnt lgkmcnt(0)
	v_add_f32_e32 v234, v120, v234
	v_add_f32_e32 v235, v121, v235
	v_add_f32_e32 v236, v122, v236
	v_add_f32_e32 v237, v123, v237
	v_add_f32_e32 v238, v116, v238
	v_add_f32_e32 v239, v117, v239
	v_add_f32_e32 v240, v118, v240
	v_add_f32_e32 v241, v119, v241
	v_cndmask_b32_e64 v230, v248, v234, s[36:37]
	v_cndmask_b32_e64 v213, v248, v235, s[48:49]
	v_cndmask_b32_e64 v231, v248, v236, s[74:75]
	v_cndmask_b32_e64 v120, v248, v237, s[76:77]
	v_cndmask_b32_e64 v123, v248, v238, s[78:79]
	v_cndmask_b32_e64 v122, v248, v239, s[82:83]
	v_cndmask_b32_e64 v117, v248, v240, s[84:85]
	v_cndmask_b32_e64 v116, v248, v241, s[86:87]
	s_mov_b64 s[40:41], exec
	s_branch .LBB0_243
